# dn_prep stage 1 l2norm: 16-lane butterfly sums via DPP adds (quad_perm/row_half_mirror/row_mirror) instead of four ds_bpermute round trips; bit-identical operands
# speedup vs baseline: 1.0010x; 1.0010x over previous
; #define LAS __attribute__((address_space(3)))
; __device__ __forceinline__ float lo_bf(unsigned w) { return __uint_as_float(w << 16); }
; __device__ __forceinline__ float hi_bf(unsigned w) { return __uint_as_float(w & 0xffff0000u); }
; __device__ __forceinline__ float silu_(float x) { return x * sigm(x); }
; __device__ __forceinline__ void dn_prep_item(const Args& a, LAS unsigned char* lds, int item, int tid, int wave, int lane, int& cwh, int next_item) {
;     ...
;         for (int jj = 0; jj < 4; ++jj) { const int pos = n * 64 + i - 3 + jj; xv[jj] = (v4u){0u, 0u, 0u, 0u};
;             if (pos >= 0) xv[jj] = *(const v4u*)(P + (size_t)(b * T + pos) * NIN + col); }
;         float o[8];
; #pragma unroll
;         for (int q = 0; q < 8; ++q) o[q] = 0.f;
; #pragma unroll
;         for (int jj = 0; jj < 4; ++jj) { const v4u v = xv[jj];
;             const f32x4 w0 = *(const LAS f32x4*)(cwl + (which * 4 + jj) * 128 + 8 * gq), w1 = *(const LAS f32x4*)(cwl + (which * 4 + jj) * 128 + 8 * gq + 4);
;             o[0] += w0[0] * lo_bf(v.x); o[1] += w0[1] * hi_bf(v.x); o[2] += w0[2] * lo_bf(v.y); o[3] += w0[3] * hi_bf(v.y);
;             o[4] += w1[0] * lo_bf(v.z); o[5] += w1[1] * hi_bf(v.z); o[6] += w1[2] * lo_bf(v.w); o[7] += w1[3] * hi_bf(v.w); }
;         float s = 0.f;
; #pragma unroll
;         for (int q = 0; q < 8; ++q) { o[q] = silu_(o[q]); s += o[q] * o[q]; }
;         s += __shfl_xor(s, 1); s += __shfl_xor(s, 2); s += __shfl_xor(s, 4); s += __shfl_xor(s, 8);
;         const float inv = which == 2 ? 1.0f : rsqrtf(s + EPS) * (which == 0 ? 0.08838834764831845f : 1.0f);
.Ls1t1_760:
	s_or_b64 exec, exec, s[22:23]
	v_or_b32_e32 v2, s39, v109
	v_mov_b64_e32 v[0:1], s[10:11]
	v_mad_u64_u32 v[0:1], s[22:23], v2, s25, v[0:1]
	v_lshl_add_u64 v[0:1], v[0:1], 0, v[56:57]
	global_load_dwordx4 v[88:91], v[0:1], off
	v_lshl_add_u32 v0, v43, 11, v150
	ds_read_b128 v[44:47], v0
	ds_read_b128 v[28:31], v0 offset:16
	ds_read_b128 v[72:75], v0 offset:512
	ds_read_b128 v[24:27], v0 offset:528
	ds_read_b128 v[76:79], v0 offset:1024
	ds_read_b128 v[12:15], v0 offset:1040
	ds_read_b128 v[80:83], v0 offset:1536
	ds_read_b128 v[0:3], v0 offset:1552
	s_waitcnt vmcnt(7)
	v_lshlrev_b32_e32 v32, 16, v16
	v_and_b32_e32 v33, 0xffff0000, v16
	s_waitcnt lgkmcnt(0)
	v_pk_fma_f32 v[32:33], v[44:45], v[32:33], 0 op_sel_hi:[1,1,0]
	s_waitcnt vmcnt(6)
	v_lshlrev_b32_e32 v34, 16, v8
	v_and_b32_e32 v35, 0xffff0000, v8
	v_pk_fma_f32 v[32:33], v[72:73], v[34:35], v[32:33]
	s_waitcnt vmcnt(5)
	v_lshlrev_b32_e32 v34, 16, v20
	v_and_b32_e32 v35, 0xffff0000, v20
	v_pk_fma_f32 v[32:33], v[76:77], v[34:35], v[32:33]
	v_lshlrev_b32_e32 v16, 16, v17
	v_and_b32_e32 v17, 0xffff0000, v17
	v_pk_fma_f32 v[16:17], v[46:47], v[16:17], 0 op_sel_hi:[1,1,0]
	v_lshlrev_b32_e32 v20, 16, v18
	v_cmp_ne_u32_e32 vcc, 2, v43
	s_waitcnt vmcnt(4)
	v_lshlrev_b32_e32 v34, 16, v4
	v_and_b32_e32 v35, 0xffff0000, v4
	v_pk_fma_f32 v[32:33], v[80:81], v[34:35], v[32:33]
	s_nop 0
	v_mul_f32_e32 v4, 0xbfb8aa3b, v32
	v_exp_f32_e32 v8, v4
	v_mov_b32_e32 v4, 1.0
	v_add_f32_e32 v8, 1.0, v8
	v_rcp_f32_e32 v34, v8
	v_mul_f32_e32 v8, 0xbfb8aa3b, v33
	v_exp_f32_e32 v8, v8
	s_nop 0
	v_add_f32_e32 v8, 1.0, v8
	v_rcp_f32_e32 v35, v8
	v_lshlrev_b32_e32 v8, 16, v9
	v_and_b32_e32 v9, 0xffff0000, v9
	v_pk_fma_f32 v[8:9], v[74:75], v[8:9], v[16:17]
	v_lshlrev_b32_e32 v16, 16, v21
	v_and_b32_e32 v17, 0xffff0000, v21
	v_pk_fma_f32 v[8:9], v[78:79], v[16:17], v[8:9]
	v_lshlrev_b32_e32 v16, 16, v5
	v_and_b32_e32 v17, 0xffff0000, v5
	v_pk_fma_f32 v[8:9], v[82:83], v[16:17], v[8:9]
	v_and_b32_e32 v21, 0xffff0000, v18
	v_mul_f32_e32 v5, 0xbfb8aa3b, v8
	v_exp_f32_e32 v5, v5
	v_pk_fma_f32 v[20:21], v[28:29], v[20:21], 0 op_sel_hi:[1,1,0]
	v_lshlrev_b32_e32 v28, 16, v10
	v_and_b32_e32 v29, 0xffff0000, v10
	v_add_f32_e32 v5, 1.0, v5
	v_rcp_f32_e32 v16, v5
	v_mul_f32_e32 v5, 0xbfb8aa3b, v9
	v_exp_f32_e32 v5, v5
	v_pk_fma_f32 v[20:21], v[24:25], v[28:29], v[20:21]
	v_lshlrev_b32_e32 v24, 16, v22
	v_and_b32_e32 v25, 0xffff0000, v22
	v_pk_fma_f32 v[12:13], v[12:13], v[24:25], v[20:21]
	v_lshlrev_b32_e32 v20, 16, v6
	v_and_b32_e32 v21, 0xffff0000, v6
	v_add_f32_e32 v5, 1.0, v5
	v_pk_fma_f32 v[0:1], v[0:1], v[20:21], v[12:13]
	v_rcp_f32_e32 v17, v5
	v_mul_f32_e32 v5, 0xbfb8aa3b, v0
	v_exp_f32_e32 v5, v5
	v_lshlrev_b32_e32 v18, 16, v19
	v_and_b32_e32 v19, 0xffff0000, v19
	v_pk_fma_f32 v[18:19], v[30:31], v[18:19], 0 op_sel_hi:[1,1,0]
	v_add_f32_e32 v5, 1.0, v5
	v_rcp_f32_e32 v12, v5
	v_mul_f32_e32 v5, 0xbfb8aa3b, v1
	v_exp_f32_e32 v5, v5
	v_lshlrev_b32_e32 v10, 16, v11
	v_and_b32_e32 v11, 0xffff0000, v11
	v_pk_fma_f32 v[10:11], v[26:27], v[10:11], v[18:19]
	v_lshlrev_b32_e32 v18, 16, v23
	v_and_b32_e32 v19, 0xffff0000, v23
	v_pk_fma_f32 v[10:11], v[14:15], v[18:19], v[10:11]
	v_lshlrev_b32_e32 v6, 16, v7
	v_and_b32_e32 v7, 0xffff0000, v7
	v_add_f32_e32 v5, 1.0, v5
	v_pk_fma_f32 v[2:3], v[2:3], v[6:7], v[10:11]
	v_rcp_f32_e32 v13, v5
	v_mul_f32_e32 v5, 0xbfb8aa3b, v2
	v_exp_f32_e32 v5, v5
	v_pk_mul_f32 v[32:33], v[32:33], v[34:35]
	v_pk_mul_f32 v[8:9], v[8:9], v[16:17]
	v_pk_mul_f32 v[34:35], v[32:33], v[32:33]
	v_add_f32_e32 v5, 1.0, v5
	v_rcp_f32_e32 v6, v5
	v_mul_f32_e32 v5, 0xbfb8aa3b, v3
	v_exp_f32_e32 v5, v5
	v_pk_mul_f32 v[16:17], v[8:9], v[8:9]
	v_pk_mul_f32 v[0:1], v[0:1], v[12:13]
	v_add_f32_e32 v5, 1.0, v5
	v_rcp_f32_e32 v7, v5
	v_add_f32_e32 v5, v34, v35
	v_add_f32_e32 v5, v16, v5
	v_pk_mul_f32 v[12:13], v[0:1], v[0:1]
	v_add_f32_e32 v5, v17, v5
	v_pk_mul_f32 v[2:3], v[2:3], v[6:7]
	v_add_f32_e32 v5, v12, v5
	v_pk_mul_f32 v[6:7], v[2:3], v[2:3]
	v_add_f32_e32 v5, v13, v5
	v_add_f32_e32 v5, v6, v5
	v_add_f32_e32 v5, v7, v5
	s_nop 1
	v_add_f32_dpp v5, v5, v5 quad_perm:[1,0,3,2] row_mask:0xf bank_mask:0xf
	s_nop 1
	v_add_f32_dpp v5, v5, v5 quad_perm:[2,3,0,1] row_mask:0xf bank_mask:0xf
	s_nop 1
	v_add_f32_dpp v5, v5, v5 row_half_mirror row_mask:0xf bank_mask:0xf
	s_nop 1
	v_mov_b32_dpp v6, v5 row_mirror row_mask:0xf bank_mask:0xf
	s_and_saveexec_b64 s[22:23], vcc
	s_cbranch_execz .Ls1t0_754
	s_waitcnt lgkmcnt(0)
	v_add_f32_e32 v4, v5, v6
	v_add_f32_e32 v4, 0x358637bd, v4
	v_mul_f32_e32 v5, 0x4b800000, v4
	v_cmp_gt_f32_e32 vcc, s34, v4
	s_nop 1
	v_cndmask_b32_e32 v4, v4, v5, vcc
	v_rsq_f32_e32 v4, v4
	s_nop 0
	v_mul_f32_e32 v5, 0x45800000, v4
	v_cndmask_b32_e32 v4, v4, v5, vcc
	v_cmp_gt_u32_e32 vcc, s30, v41
	s_nop 1
	v_cndmask_b32_e32 v5, 1.0, v231, vcc
	v_mul_f32_e32 v4, v5, v4

; #define LAS __attribute__((address_space(3)))
; __device__ __forceinline__ float lo_bf(unsigned w) { return __uint_as_float(w << 16); }
; __device__ __forceinline__ float hi_bf(unsigned w) { return __uint_as_float(w & 0xffff0000u); }
; __device__ __forceinline__ float silu_(float x) { return x * sigm(x); }
; __device__ __forceinline__ void dn_prep_item(const Args& a, LAS unsigned char* lds, int item, int tid, int wave, int lane, int& cwh, int next_item) {
;     ...
;         for (int jj = 0; jj < 4; ++jj) { const v4u v = xv[jj];
;             const f32x4 w0 = *(const LAS f32x4*)(cwl + (which * 4 + jj) * 128 + 8 * gq), w1 = *(const LAS f32x4*)(cwl + (which * 4 + jj) * 128 + 8 * gq + 4);
;             o[0] += w0[0] * lo_bf(v.x); o[1] += w0[1] * hi_bf(v.x); o[2] += w0[2] * lo_bf(v.y); o[3] += w0[3] * hi_bf(v.y);
;             o[4] += w1[0] * lo_bf(v.z); o[5] += w1[1] * hi_bf(v.z); o[6] += w1[2] * lo_bf(v.w); o[7] += w1[3] * hi_bf(v.w); }
;         float s = 0.f;
; #pragma unroll
;         for (int q = 0; q < 8; ++q) { o[q] = silu_(o[q]); s += o[q] * o[q]; }
;         s += __shfl_xor(s, 1); s += __shfl_xor(s, 2); s += __shfl_xor(s, 4); s += __shfl_xor(s, 8);
;         const float inv = which == 2 ? 1.0f : rsqrtf(s + EPS) * (which == 0 ? 0.08838834764831845f : 1.0f);
.Ls1t2_768:
	s_or_b64 exec, exec, s[22:23]
	v_or_b32_e32 v2, s39, v42
	v_mov_b64_e32 v[0:1], s[10:11]
	v_mad_u64_u32 v[0:1], s[22:23], v2, s25, v[0:1]
	v_lshl_add_u64 v[0:1], v[0:1], 0, v[56:57]
	global_load_dwordx4 v[4:7], v[0:1], off
	v_lshl_add_u32 v0, v110, 11, v150
	ds_read_b128 v[72:75], v0
	ds_read_b128 v[28:31], v0 offset:16
	ds_read_b128 v[76:79], v0 offset:512
	ds_read_b128 v[24:27], v0 offset:528
	ds_read_b128 v[80:83], v0 offset:1024
	ds_read_b128 v[96:99], v0 offset:1040
	ds_read_b128 v[84:87], v0 offset:1536
	ds_read_b128 v[0:3], v0 offset:1552
	s_waitcnt vmcnt(7)
	v_lshlrev_b32_e32 v32, 16, v100
	v_and_b32_e32 v33, 0xffff0000, v100
	s_waitcnt lgkmcnt(7)
	v_pk_fma_f32 v[32:33], v[72:73], v[32:33], 0 op_sel_hi:[1,1,0]
	s_waitcnt vmcnt(6)
	v_lshlrev_b32_e32 v34, 16, v92
	v_and_b32_e32 v35, 0xffff0000, v92
	s_waitcnt lgkmcnt(5)
	v_pk_fma_f32 v[32:33], v[76:77], v[34:35], v[32:33]
	s_waitcnt vmcnt(5)
	v_lshlrev_b32_e32 v34, 16, v104
	v_and_b32_e32 v35, 0xffff0000, v104
	s_waitcnt lgkmcnt(3)
	v_pk_fma_f32 v[32:33], v[80:81], v[34:35], v[32:33]
	v_lshlrev_b32_e32 v100, 16, v101
	v_and_b32_e32 v101, 0xffff0000, v101
	v_pk_fma_f32 v[100:101], v[74:75], v[100:101], 0 op_sel_hi:[1,1,0]
	v_lshlrev_b32_e32 v104, 16, v102
	v_cmp_ne_u32_e32 vcc, 2, v110
	s_waitcnt vmcnt(4)
	v_lshlrev_b32_e32 v34, 16, v88
	v_and_b32_e32 v35, 0xffff0000, v88
	s_waitcnt lgkmcnt(1)
	v_pk_fma_f32 v[32:33], v[84:85], v[34:35], v[32:33]
	s_nop 0
	v_mul_f32_e32 v88, 0xbfb8aa3b, v32
	v_exp_f32_e32 v92, v88
	v_mov_b32_e32 v88, 1.0
	v_add_f32_e32 v92, 1.0, v92
	v_rcp_f32_e32 v34, v92
	v_mul_f32_e32 v92, 0xbfb8aa3b, v33
	v_exp_f32_e32 v92, v92
	s_nop 0
	v_add_f32_e32 v92, 1.0, v92
	v_rcp_f32_e32 v35, v92
	v_lshlrev_b32_e32 v92, 16, v93
	v_and_b32_e32 v93, 0xffff0000, v93
	v_pk_fma_f32 v[92:93], v[78:79], v[92:93], v[100:101]
	v_lshlrev_b32_e32 v100, 16, v105
	v_and_b32_e32 v101, 0xffff0000, v105
	v_pk_fma_f32 v[92:93], v[82:83], v[100:101], v[92:93]
	v_lshlrev_b32_e32 v100, 16, v89
	v_and_b32_e32 v101, 0xffff0000, v89
	v_pk_fma_f32 v[92:93], v[86:87], v[100:101], v[92:93]
	v_and_b32_e32 v105, 0xffff0000, v102
	v_mul_f32_e32 v89, 0xbfb8aa3b, v92
	v_exp_f32_e32 v89, v89
	v_pk_fma_f32 v[104:105], v[28:29], v[104:105], 0 op_sel_hi:[1,1,0]
	v_lshlrev_b32_e32 v28, 16, v94
	v_and_b32_e32 v29, 0xffff0000, v94
	v_add_f32_e32 v89, 1.0, v89
	v_rcp_f32_e32 v100, v89
	v_mul_f32_e32 v89, 0xbfb8aa3b, v93
	v_exp_f32_e32 v89, v89
	v_pk_fma_f32 v[104:105], v[24:25], v[28:29], v[104:105]
	v_lshlrev_b32_e32 v24, 16, v106
	v_and_b32_e32 v25, 0xffff0000, v106
	v_pk_fma_f32 v[96:97], v[96:97], v[24:25], v[104:105]
	v_lshlrev_b32_e32 v104, 16, v90
	v_and_b32_e32 v105, 0xffff0000, v90
	v_add_f32_e32 v89, 1.0, v89
	s_waitcnt lgkmcnt(0)
	v_pk_fma_f32 v[0:1], v[0:1], v[104:105], v[96:97]
	v_rcp_f32_e32 v101, v89
	v_mul_f32_e32 v89, 0xbfb8aa3b, v0
	v_exp_f32_e32 v89, v89
	v_lshlrev_b32_e32 v102, 16, v103
	v_and_b32_e32 v103, 0xffff0000, v103
	v_pk_fma_f32 v[102:103], v[30:31], v[102:103], 0 op_sel_hi:[1,1,0]
	v_add_f32_e32 v89, 1.0, v89
	v_rcp_f32_e32 v96, v89
	v_mul_f32_e32 v89, 0xbfb8aa3b, v1
	v_exp_f32_e32 v89, v89
	v_lshlrev_b32_e32 v94, 16, v95
	v_and_b32_e32 v95, 0xffff0000, v95
	v_pk_fma_f32 v[94:95], v[26:27], v[94:95], v[102:103]
	v_lshlrev_b32_e32 v102, 16, v107
	v_and_b32_e32 v103, 0xffff0000, v107
	v_pk_fma_f32 v[94:95], v[98:99], v[102:103], v[94:95]
	v_lshlrev_b32_e32 v90, 16, v91
	v_and_b32_e32 v91, 0xffff0000, v91
	v_add_f32_e32 v89, 1.0, v89
	v_pk_fma_f32 v[2:3], v[2:3], v[90:91], v[94:95]
	v_rcp_f32_e32 v97, v89
	v_mul_f32_e32 v89, 0xbfb8aa3b, v2
	v_exp_f32_e32 v89, v89
	v_pk_mul_f32 v[32:33], v[32:33], v[34:35]
	v_pk_mul_f32 v[92:93], v[92:93], v[100:101]
	v_pk_mul_f32 v[34:35], v[32:33], v[32:33]
	v_add_f32_e32 v89, 1.0, v89
	v_rcp_f32_e32 v90, v89
	v_mul_f32_e32 v89, 0xbfb8aa3b, v3
	v_exp_f32_e32 v89, v89
	v_pk_mul_f32 v[100:101], v[92:93], v[92:93]
	v_pk_mul_f32 v[0:1], v[0:1], v[96:97]
	v_add_f32_e32 v89, 1.0, v89
	v_rcp_f32_e32 v91, v89
	v_add_f32_e32 v89, v34, v35
	v_add_f32_e32 v89, v100, v89
	v_pk_mul_f32 v[96:97], v[0:1], v[0:1]
	v_add_f32_e32 v89, v101, v89
	v_pk_mul_f32 v[2:3], v[2:3], v[90:91]
	v_add_f32_e32 v89, v96, v89
	v_pk_mul_f32 v[90:91], v[2:3], v[2:3]
	v_add_f32_e32 v89, v97, v89
	v_add_f32_e32 v89, v90, v89
	v_add_f32_e32 v89, v91, v89
	s_nop 1
	v_add_f32_dpp v89, v89, v89 quad_perm:[1,0,3,2] row_mask:0xf bank_mask:0xf
	s_nop 1
	v_add_f32_dpp v89, v89, v89 quad_perm:[2,3,0,1] row_mask:0xf bank_mask:0xf
	s_nop 1
	v_add_f32_dpp v89, v89, v89 row_half_mirror row_mask:0xf bank_mask:0xf
	s_nop 1
	v_mov_b32_dpp v90, v89 row_mirror row_mask:0xf bank_mask:0xf
	s_and_saveexec_b64 s[22:23], vcc
	s_cbranch_execz .Ls1t1_762
	s_waitcnt lgkmcnt(0)
	v_add_f32_e32 v88, v89, v90
	v_add_f32_e32 v88, 0x358637bd, v88
	v_mul_f32_e32 v89, 0x4b800000, v88
	v_cmp_gt_f32_e32 vcc, s34, v88
	s_nop 1
	v_cndmask_b32_e32 v88, v88, v89, vcc
	v_rsq_f32_e32 v88, v88
	s_nop 0
	v_mul_f32_e32 v89, 0x45800000, v88
	v_cndmask_b32_e32 v88, v88, v89, vcc
	v_cmp_gt_u32_e32 vcc, s30, v108
	s_nop 1
	v_cndmask_b32_e32 v89, 1.0, v231, vcc
	v_mul_f32_e32 v88, v89, v88

; #define LAS __attribute__((address_space(3)))
; __device__ __forceinline__ float lo_bf(unsigned w) { return __uint_as_float(w << 16); }
; __device__ __forceinline__ float hi_bf(unsigned w) { return __uint_as_float(w & 0xffff0000u); }
; __device__ __forceinline__ float silu_(float x) { return x * sigm(x); }
; __device__ __forceinline__ void dn_prep_item(const Args& a, LAS unsigned char* lds, int item, int tid, int wave, int lane, int& cwh, int next_item) {
;     ...
;         for (int jj = 0; jj < 4; ++jj) { const int pos = n * 64 + i - 3 + jj; xv[jj] = (v4u){0u, 0u, 0u, 0u};
;             if (pos >= 0) xv[jj] = *(const v4u*)(P + (size_t)(b * T + pos) * NIN + col); }
;         float o[8];
; #pragma unroll
;         for (int q = 0; q < 8; ++q) o[q] = 0.f;
; #pragma unroll
;         for (int jj = 0; jj < 4; ++jj) { const v4u v = xv[jj];
;             const f32x4 w0 = *(const LAS f32x4*)(cwl + (which * 4 + jj) * 128 + 8 * gq), w1 = *(const LAS f32x4*)(cwl + (which * 4 + jj) * 128 + 8 * gq + 4);
;             o[0] += w0[0] * lo_bf(v.x); o[1] += w0[1] * hi_bf(v.x); o[2] += w0[2] * lo_bf(v.y); o[3] += w0[3] * hi_bf(v.y);
;             o[4] += w1[0] * lo_bf(v.z); o[5] += w1[1] * hi_bf(v.z); o[6] += w1[2] * lo_bf(v.w); o[7] += w1[3] * hi_bf(v.w); }
;         float s = 0.f;
; #pragma unroll
;         for (int q = 0; q < 8; ++q) { o[q] = silu_(o[q]); s += o[q] * o[q]; }
;         s += __shfl_xor(s, 1); s += __shfl_xor(s, 2); s += __shfl_xor(s, 4); s += __shfl_xor(s, 8);
;         const float inv = which == 2 ? 1.0f : rsqrtf(s + EPS) * (which == 0 ? 0.08838834764831845f : 1.0f);
.Ls1t3_752:
	s_or_b64 exec, exec, s[22:23]
	v_or_b32_e32 v2, s39, v108
	v_mov_b64_e32 v[0:1], s[10:11]
	v_mad_u64_u32 v[0:1], s[22:23], v2, s25, v[0:1]
	v_lshl_add_u64 v[0:1], v[0:1], 0, v[56:57]
	global_load_dwordx4 v[88:91], v[0:1], off
	v_lshl_add_u32 v0, v43, 11, v150
	ds_read_b128 v[44:47], v0
	ds_read_b128 v[28:31], v0 offset:16
	ds_read_b128 v[72:75], v0 offset:512
	ds_read_b128 v[24:27], v0 offset:528
	ds_read_b128 v[76:79], v0 offset:1024
	ds_read_b128 v[12:15], v0 offset:1040
	ds_read_b128 v[80:83], v0 offset:1536
	ds_read_b128 v[0:3], v0 offset:1552
	s_waitcnt vmcnt(7)
	v_lshlrev_b32_e32 v32, 16, v16
	v_and_b32_e32 v33, 0xffff0000, v16
	s_waitcnt lgkmcnt(7)
	v_pk_fma_f32 v[32:33], v[44:45], v[32:33], 0 op_sel_hi:[1,1,0]
	s_waitcnt vmcnt(6)
	v_lshlrev_b32_e32 v34, 16, v8
	v_and_b32_e32 v35, 0xffff0000, v8
	s_waitcnt lgkmcnt(5)
	v_pk_fma_f32 v[32:33], v[72:73], v[34:35], v[32:33]
	s_waitcnt vmcnt(5)
	v_lshlrev_b32_e32 v34, 16, v20
	v_and_b32_e32 v35, 0xffff0000, v20
	s_waitcnt lgkmcnt(3)
	v_pk_fma_f32 v[32:33], v[76:77], v[34:35], v[32:33]
	v_lshlrev_b32_e32 v16, 16, v17
	v_and_b32_e32 v17, 0xffff0000, v17
	v_pk_fma_f32 v[16:17], v[46:47], v[16:17], 0 op_sel_hi:[1,1,0]
	v_lshlrev_b32_e32 v20, 16, v18
	v_cmp_ne_u32_e32 vcc, 2, v43
	s_waitcnt vmcnt(4)
	v_lshlrev_b32_e32 v34, 16, v4
	v_and_b32_e32 v35, 0xffff0000, v4
	s_waitcnt lgkmcnt(1)
	v_pk_fma_f32 v[32:33], v[80:81], v[34:35], v[32:33]
	s_nop 0
	v_mul_f32_e32 v4, 0xbfb8aa3b, v32
	v_exp_f32_e32 v8, v4
	v_mov_b32_e32 v4, 1.0
	v_add_f32_e32 v8, 1.0, v8
	v_rcp_f32_e32 v34, v8
	v_mul_f32_e32 v8, 0xbfb8aa3b, v33
	v_exp_f32_e32 v8, v8
	s_nop 0
	v_add_f32_e32 v8, 1.0, v8
	v_rcp_f32_e32 v35, v8
	v_lshlrev_b32_e32 v8, 16, v9
	v_and_b32_e32 v9, 0xffff0000, v9
	v_pk_fma_f32 v[8:9], v[74:75], v[8:9], v[16:17]
	v_lshlrev_b32_e32 v16, 16, v21
	v_and_b32_e32 v17, 0xffff0000, v21
	v_pk_fma_f32 v[8:9], v[78:79], v[16:17], v[8:9]
	v_lshlrev_b32_e32 v16, 16, v5
	v_and_b32_e32 v17, 0xffff0000, v5
	v_pk_fma_f32 v[8:9], v[82:83], v[16:17], v[8:9]
	v_and_b32_e32 v21, 0xffff0000, v18
	v_mul_f32_e32 v5, 0xbfb8aa3b, v8
	v_exp_f32_e32 v5, v5
	v_pk_fma_f32 v[20:21], v[28:29], v[20:21], 0 op_sel_hi:[1,1,0]
	v_lshlrev_b32_e32 v28, 16, v10
	v_and_b32_e32 v29, 0xffff0000, v10
	v_add_f32_e32 v5, 1.0, v5
	v_rcp_f32_e32 v16, v5
	v_mul_f32_e32 v5, 0xbfb8aa3b, v9
	v_exp_f32_e32 v5, v5
	v_pk_fma_f32 v[20:21], v[24:25], v[28:29], v[20:21]
	v_lshlrev_b32_e32 v24, 16, v22
	v_and_b32_e32 v25, 0xffff0000, v22
	v_pk_fma_f32 v[12:13], v[12:13], v[24:25], v[20:21]
	v_lshlrev_b32_e32 v20, 16, v6
	v_and_b32_e32 v21, 0xffff0000, v6
	v_add_f32_e32 v5, 1.0, v5
	s_waitcnt lgkmcnt(0)
	v_pk_fma_f32 v[0:1], v[0:1], v[20:21], v[12:13]
	v_rcp_f32_e32 v17, v5
	v_mul_f32_e32 v5, 0xbfb8aa3b, v0
	v_exp_f32_e32 v5, v5
	v_lshlrev_b32_e32 v18, 16, v19
	v_and_b32_e32 v19, 0xffff0000, v19
	v_pk_fma_f32 v[18:19], v[30:31], v[18:19], 0 op_sel_hi:[1,1,0]
	v_add_f32_e32 v5, 1.0, v5
	v_rcp_f32_e32 v12, v5
	v_mul_f32_e32 v5, 0xbfb8aa3b, v1
	v_exp_f32_e32 v5, v5
	v_lshlrev_b32_e32 v10, 16, v11
	v_and_b32_e32 v11, 0xffff0000, v11
	v_pk_fma_f32 v[10:11], v[26:27], v[10:11], v[18:19]
	v_lshlrev_b32_e32 v18, 16, v23
	v_and_b32_e32 v19, 0xffff0000, v23
	v_pk_fma_f32 v[10:11], v[14:15], v[18:19], v[10:11]
	v_lshlrev_b32_e32 v6, 16, v7
	v_and_b32_e32 v7, 0xffff0000, v7
	v_add_f32_e32 v5, 1.0, v5
	v_pk_fma_f32 v[2:3], v[2:3], v[6:7], v[10:11]
	v_rcp_f32_e32 v13, v5
	v_mul_f32_e32 v5, 0xbfb8aa3b, v2
	v_exp_f32_e32 v5, v5
	v_pk_mul_f32 v[32:33], v[32:33], v[34:35]
	v_pk_mul_f32 v[8:9], v[8:9], v[16:17]
	v_pk_mul_f32 v[34:35], v[32:33], v[32:33]
	v_add_f32_e32 v5, 1.0, v5
	v_rcp_f32_e32 v6, v5
	v_mul_f32_e32 v5, 0xbfb8aa3b, v3
	v_exp_f32_e32 v5, v5
	v_pk_mul_f32 v[16:17], v[8:9], v[8:9]
	v_pk_mul_f32 v[0:1], v[0:1], v[12:13]
	v_add_f32_e32 v5, 1.0, v5
	v_rcp_f32_e32 v7, v5
	v_add_f32_e32 v5, v34, v35
	v_add_f32_e32 v5, v16, v5
	v_pk_mul_f32 v[12:13], v[0:1], v[0:1]
	v_add_f32_e32 v5, v17, v5
	v_pk_mul_f32 v[2:3], v[2:3], v[6:7]
	v_add_f32_e32 v5, v12, v5
	v_pk_mul_f32 v[6:7], v[2:3], v[2:3]
	v_add_f32_e32 v5, v13, v5
	v_add_f32_e32 v5, v6, v5
	v_add_f32_e32 v5, v7, v5
	s_nop 1
	v_add_f32_dpp v5, v5, v5 quad_perm:[1,0,3,2] row_mask:0xf bank_mask:0xf
	s_nop 1
	v_add_f32_dpp v5, v5, v5 quad_perm:[2,3,0,1] row_mask:0xf bank_mask:0xf
	s_nop 1
	v_add_f32_dpp v5, v5, v5 row_half_mirror row_mask:0xf bank_mask:0xf
	s_nop 1
	v_mov_b32_dpp v6, v5 row_mirror row_mask:0xf bank_mask:0xf
	s_and_saveexec_b64 s[22:23], vcc
	s_cbranch_execz .Ls1t2_745
	s_waitcnt lgkmcnt(0)
	v_add_f32_e32 v4, v5, v6
	v_add_f32_e32 v4, 0x358637bd, v4
	v_mul_f32_e32 v5, 0x4b800000, v4
	v_cmp_gt_f32_e32 vcc, s34, v4
	s_nop 1
	v_cndmask_b32_e32 v4, v4, v5, vcc
	v_rsq_f32_e32 v4, v4
	s_nop 0
	v_mul_f32_e32 v5, 0x45800000, v4
	v_cndmask_b32_e32 v4, v4, v5, vcc

; #define LAS __attribute__((address_space(3)))
; __device__ __forceinline__ float lo_bf(unsigned w) { return __uint_as_float(w << 16); }
; __device__ __forceinline__ float hi_bf(unsigned w) { return __uint_as_float(w & 0xffff0000u); }
; __device__ __forceinline__ float silu_(float x) { return x * sigm(x); }
; __device__ __forceinline__ void dn_prep_item(const Args& a, LAS unsigned char* lds, int item, int tid, int wave, int lane, int& cwh, int next_item) {
;     ...
;         for (int jj = 0; jj < 4; ++jj) { const int pos = n * 64 + i - 3 + jj; xv[jj] = (v4u){0u, 0u, 0u, 0u};
;             if (pos >= 0) xv[jj] = *(const v4u*)(P + (size_t)(b * T + pos) * NIN + col); }
;         float o[8];
; #pragma unroll
;         for (int q = 0; q < 8; ++q) o[q] = 0.f;
; #pragma unroll
;         for (int jj = 0; jj < 4; ++jj) { const v4u v = xv[jj];
;             const f32x4 w0 = *(const LAS f32x4*)(cwl + (which * 4 + jj) * 128 + 8 * gq), w1 = *(const LAS f32x4*)(cwl + (which * 4 + jj) * 128 + 8 * gq + 4);
;             o[0] += w0[0] * lo_bf(v.x); o[1] += w0[1] * hi_bf(v.x); o[2] += w0[2] * lo_bf(v.y); o[3] += w0[3] * hi_bf(v.y);
;             o[4] += w1[0] * lo_bf(v.z); o[5] += w1[1] * hi_bf(v.z); o[6] += w1[2] * lo_bf(v.w); o[7] += w1[3] * hi_bf(v.w); }
;         float s = 0.f;
; #pragma unroll
;         for (int q = 0; q < 8; ++q) { o[q] = silu_(o[q]); s += o[q] * o[q]; }
;         s += __shfl_xor(s, 1); s += __shfl_xor(s, 2); s += __shfl_xor(s, 4); s += __shfl_xor(s, 8);
;         const float inv = which == 2 ? 1.0f : rsqrtf(s + EPS) * (which == 0 ? 0.08838834764831845f : 1.0f);
.Ls1t4_760:
	s_or_b64 exec, exec, s[22:23]
	v_or_b32_e32 v2, s39, v113
	v_mov_b64_e32 v[0:1], s[10:11]
	v_mad_u64_u32 v[0:1], s[22:23], v2, s25, v[0:1]
	v_lshl_add_u64 v[0:1], v[0:1], 0, v[56:57]
	global_load_dwordx4 v[4:7], v[0:1], off
	v_lshl_add_u32 v0, v109, 11, v150
	ds_read_b128 v[44:47], v0
	ds_read_b128 v[28:31], v0 offset:16
	ds_read_b128 v[72:75], v0 offset:512
	ds_read_b128 v[24:27], v0 offset:528
	ds_read_b128 v[76:79], v0 offset:1024
	ds_read_b128 v[96:99], v0 offset:1040
	ds_read_b128 v[80:83], v0 offset:1536
	ds_read_b128 v[0:3], v0 offset:1552
	s_waitcnt vmcnt(7)
	v_lshlrev_b32_e32 v32, 16, v100
	v_and_b32_e32 v33, 0xffff0000, v100
	s_waitcnt lgkmcnt(0)
	v_pk_fma_f32 v[32:33], v[44:45], v[32:33], 0 op_sel_hi:[1,1,0]
	s_waitcnt vmcnt(6)
	v_lshlrev_b32_e32 v34, 16, v92
	v_and_b32_e32 v35, 0xffff0000, v92
	v_pk_fma_f32 v[32:33], v[72:73], v[34:35], v[32:33]
	s_waitcnt vmcnt(5)
	v_lshlrev_b32_e32 v34, 16, v104
	v_and_b32_e32 v35, 0xffff0000, v104
	v_pk_fma_f32 v[32:33], v[76:77], v[34:35], v[32:33]
	v_lshlrev_b32_e32 v100, 16, v101
	v_and_b32_e32 v101, 0xffff0000, v101
	v_pk_fma_f32 v[100:101], v[46:47], v[100:101], 0 op_sel_hi:[1,1,0]
	v_lshlrev_b32_e32 v104, 16, v102
	v_cmp_ne_u32_e32 vcc, 2, v109
	s_waitcnt vmcnt(4)
	v_lshlrev_b32_e32 v34, 16, v88
	v_and_b32_e32 v35, 0xffff0000, v88
	v_pk_fma_f32 v[32:33], v[80:81], v[34:35], v[32:33]
	s_nop 0
	v_mul_f32_e32 v88, 0xbfb8aa3b, v32
	v_exp_f32_e32 v92, v88
	v_mov_b32_e32 v88, 1.0
	v_add_f32_e32 v92, 1.0, v92
	v_rcp_f32_e32 v34, v92
	v_mul_f32_e32 v92, 0xbfb8aa3b, v33
	v_exp_f32_e32 v92, v92
	s_nop 0
	v_add_f32_e32 v92, 1.0, v92
	v_rcp_f32_e32 v35, v92
	v_lshlrev_b32_e32 v92, 16, v93
	v_and_b32_e32 v93, 0xffff0000, v93
	v_pk_fma_f32 v[92:93], v[74:75], v[92:93], v[100:101]
	v_lshlrev_b32_e32 v100, 16, v105
	v_and_b32_e32 v101, 0xffff0000, v105
	v_pk_fma_f32 v[92:93], v[78:79], v[100:101], v[92:93]
	v_lshlrev_b32_e32 v100, 16, v89
	v_and_b32_e32 v101, 0xffff0000, v89
	v_pk_fma_f32 v[92:93], v[82:83], v[100:101], v[92:93]
	v_and_b32_e32 v105, 0xffff0000, v102
	v_mul_f32_e32 v89, 0xbfb8aa3b, v92
	v_exp_f32_e32 v89, v89
	v_pk_fma_f32 v[104:105], v[28:29], v[104:105], 0 op_sel_hi:[1,1,0]
	v_lshlrev_b32_e32 v28, 16, v94
	v_and_b32_e32 v29, 0xffff0000, v94
	v_add_f32_e32 v89, 1.0, v89
	v_rcp_f32_e32 v100, v89
	v_mul_f32_e32 v89, 0xbfb8aa3b, v93
	v_exp_f32_e32 v89, v89
	v_pk_fma_f32 v[104:105], v[24:25], v[28:29], v[104:105]
	v_lshlrev_b32_e32 v24, 16, v106
	v_and_b32_e32 v25, 0xffff0000, v106
	v_pk_fma_f32 v[96:97], v[96:97], v[24:25], v[104:105]
	v_lshlrev_b32_e32 v104, 16, v90
	v_and_b32_e32 v105, 0xffff0000, v90
	v_add_f32_e32 v89, 1.0, v89
	v_pk_fma_f32 v[0:1], v[0:1], v[104:105], v[96:97]
	v_rcp_f32_e32 v101, v89
	v_mul_f32_e32 v89, 0xbfb8aa3b, v0
	v_exp_f32_e32 v89, v89
	v_lshlrev_b32_e32 v102, 16, v103
	v_and_b32_e32 v103, 0xffff0000, v103
	v_pk_fma_f32 v[102:103], v[30:31], v[102:103], 0 op_sel_hi:[1,1,0]
	v_add_f32_e32 v89, 1.0, v89
	v_rcp_f32_e32 v96, v89
	v_mul_f32_e32 v89, 0xbfb8aa3b, v1
	v_exp_f32_e32 v89, v89
	v_lshlrev_b32_e32 v94, 16, v95
	v_and_b32_e32 v95, 0xffff0000, v95
	v_pk_fma_f32 v[94:95], v[26:27], v[94:95], v[102:103]
	v_lshlrev_b32_e32 v102, 16, v107
	v_and_b32_e32 v103, 0xffff0000, v107
	v_pk_fma_f32 v[94:95], v[98:99], v[102:103], v[94:95]
	v_lshlrev_b32_e32 v90, 16, v91
	v_and_b32_e32 v91, 0xffff0000, v91
	v_add_f32_e32 v89, 1.0, v89
	v_pk_fma_f32 v[2:3], v[2:3], v[90:91], v[94:95]
	v_rcp_f32_e32 v97, v89
	v_mul_f32_e32 v89, 0xbfb8aa3b, v2
	v_exp_f32_e32 v89, v89
	v_pk_mul_f32 v[32:33], v[32:33], v[34:35]
	v_pk_mul_f32 v[92:93], v[92:93], v[100:101]
	v_pk_mul_f32 v[34:35], v[32:33], v[32:33]
	v_add_f32_e32 v89, 1.0, v89
	v_rcp_f32_e32 v90, v89
	v_mul_f32_e32 v89, 0xbfb8aa3b, v3
	v_exp_f32_e32 v89, v89
	v_pk_mul_f32 v[100:101], v[92:93], v[92:93]
	v_pk_mul_f32 v[0:1], v[0:1], v[96:97]
	v_add_f32_e32 v89, 1.0, v89
	v_rcp_f32_e32 v91, v89
	v_add_f32_e32 v89, v34, v35
	v_add_f32_e32 v89, v100, v89
	v_pk_mul_f32 v[96:97], v[0:1], v[0:1]
	v_add_f32_e32 v89, v101, v89
	v_pk_mul_f32 v[2:3], v[2:3], v[90:91]
	v_add_f32_e32 v89, v96, v89
	v_pk_mul_f32 v[90:91], v[2:3], v[2:3]
	v_add_f32_e32 v89, v97, v89
	v_add_f32_e32 v89, v90, v89
	v_add_f32_e32 v89, v91, v89
	s_nop 1
	v_add_f32_dpp v89, v89, v89 quad_perm:[1,0,3,2] row_mask:0xf bank_mask:0xf
	s_nop 1
	v_add_f32_dpp v89, v89, v89 quad_perm:[2,3,0,1] row_mask:0xf bank_mask:0xf
	s_nop 1
	v_add_f32_dpp v89, v89, v89 row_half_mirror row_mask:0xf bank_mask:0xf
	s_nop 1
	v_mov_b32_dpp v90, v89 row_mirror row_mask:0xf bank_mask:0xf
	s_and_saveexec_b64 s[22:23], vcc
	s_cbranch_execz .Ls1t3_754
	s_waitcnt lgkmcnt(0)
	v_add_f32_e32 v88, v89, v90
	v_add_f32_e32 v88, 0x358637bd, v88
	v_mul_f32_e32 v89, 0x4b800000, v88
	v_cmp_gt_f32_e32 vcc, s34, v88
	s_nop 1
	v_cndmask_b32_e32 v88, v88, v89, vcc
	v_rsq_f32_e32 v88, v88
	s_nop 0
	v_mul_f32_e32 v89, 0x45800000, v88
	v_cndmask_b32_e32 v88, v88, v89, vcc
	v_cmp_gt_u32_e32 vcc, s30, v111
	s_nop 1
	v_cndmask_b32_e32 v89, 1.0, v231, vcc
	v_mul_f32_e32 v88, v89, v88

; #define LAS __attribute__((address_space(3)))
; __device__ __forceinline__ float lo_bf(unsigned w) { return __uint_as_float(w << 16); }
; __device__ __forceinline__ float hi_bf(unsigned w) { return __uint_as_float(w & 0xffff0000u); }
; __device__ __forceinline__ float silu_(float x) { return x * sigm(x); }
; __device__ __forceinline__ void dn_prep_item(const Args& a, LAS unsigned char* lds, int item, int tid, int wave, int lane, int& cwh, int next_item) {
;     ...
;         for (int jj = 0; jj < 4; ++jj) { const int pos = n * 64 + i - 3 + jj; xv[jj] = (v4u){0u, 0u, 0u, 0u};
;             if (pos >= 0) xv[jj] = *(const v4u*)(P + (size_t)(b * T + pos) * NIN + col); }
;         float o[8];
; #pragma unroll
;         for (int q = 0; q < 8; ++q) o[q] = 0.f;
; #pragma unroll
;         for (int jj = 0; jj < 4; ++jj) { const v4u v = xv[jj];
;             const f32x4 w0 = *(const LAS f32x4*)(cwl + (which * 4 + jj) * 128 + 8 * gq), w1 = *(const LAS f32x4*)(cwl + (which * 4 + jj) * 128 + 8 * gq + 4);
;             o[0] += w0[0] * lo_bf(v.x); o[1] += w0[1] * hi_bf(v.x); o[2] += w0[2] * lo_bf(v.y); o[3] += w0[3] * hi_bf(v.y);
;             o[4] += w1[0] * lo_bf(v.z); o[5] += w1[1] * hi_bf(v.z); o[6] += w1[2] * lo_bf(v.w); o[7] += w1[3] * hi_bf(v.w); }
;         float s = 0.f;
; #pragma unroll
;         for (int q = 0; q < 8; ++q) { o[q] = silu_(o[q]); s += o[q] * o[q]; }
;         s += __shfl_xor(s, 1); s += __shfl_xor(s, 2); s += __shfl_xor(s, 4); s += __shfl_xor(s, 8);
;         const float inv = which == 2 ? 1.0f : rsqrtf(s + EPS) * (which == 0 ? 0.08838834764831845f : 1.0f);
.Ls1t5_768:
	s_or_b64 exec, exec, s[22:23]
	v_or_b32_e32 v2, s39, v108
	v_mov_b64_e32 v[0:1], s[10:11]
	v_mad_u64_u32 v[0:1], s[22:23], v2, s25, v[0:1]
	v_lshl_add_u64 v[0:1], v[0:1], 0, v[56:57]
	global_load_dwordx4 v[88:91], v[0:1], off
	v_lshl_add_u32 v0, v114, 11, v150
	ds_read_b128 v[72:75], v0
	ds_read_b128 v[28:31], v0 offset:16
	ds_read_b128 v[76:79], v0 offset:512
	ds_read_b128 v[24:27], v0 offset:528
	ds_read_b128 v[80:83], v0 offset:1024
	ds_read_b128 v[12:15], v0 offset:1040
	ds_read_b128 v[84:87], v0 offset:1536
	ds_read_b128 v[0:3], v0 offset:1552
	s_waitcnt vmcnt(7)
	v_lshlrev_b32_e32 v32, 16, v16
	v_and_b32_e32 v33, 0xffff0000, v16
	s_waitcnt lgkmcnt(7)
	v_pk_fma_f32 v[32:33], v[72:73], v[32:33], 0 op_sel_hi:[1,1,0]
	s_waitcnt vmcnt(6)
	v_lshlrev_b32_e32 v34, 16, v8
	v_and_b32_e32 v35, 0xffff0000, v8
	s_waitcnt lgkmcnt(5)
	v_pk_fma_f32 v[32:33], v[76:77], v[34:35], v[32:33]
	s_waitcnt vmcnt(5)
	v_lshlrev_b32_e32 v34, 16, v20
	v_and_b32_e32 v35, 0xffff0000, v20
	s_waitcnt lgkmcnt(3)
	v_pk_fma_f32 v[32:33], v[80:81], v[34:35], v[32:33]
	v_lshlrev_b32_e32 v16, 16, v17
	v_and_b32_e32 v17, 0xffff0000, v17
	v_pk_fma_f32 v[16:17], v[74:75], v[16:17], 0 op_sel_hi:[1,1,0]
	v_lshlrev_b32_e32 v20, 16, v18
	v_cmp_ne_u32_e32 vcc, 2, v114
	s_waitcnt vmcnt(4)
	v_lshlrev_b32_e32 v34, 16, v4
	v_and_b32_e32 v35, 0xffff0000, v4
	s_waitcnt lgkmcnt(1)
	v_pk_fma_f32 v[32:33], v[84:85], v[34:35], v[32:33]
	s_nop 0
	v_mul_f32_e32 v4, 0xbfb8aa3b, v32
	v_exp_f32_e32 v8, v4
	v_mov_b32_e32 v4, 1.0
	v_add_f32_e32 v8, 1.0, v8
	v_rcp_f32_e32 v34, v8
	v_mul_f32_e32 v8, 0xbfb8aa3b, v33
	v_exp_f32_e32 v8, v8
	s_nop 0
	v_add_f32_e32 v8, 1.0, v8
	v_rcp_f32_e32 v35, v8
	v_lshlrev_b32_e32 v8, 16, v9
	v_and_b32_e32 v9, 0xffff0000, v9
	v_pk_fma_f32 v[8:9], v[78:79], v[8:9], v[16:17]
	v_lshlrev_b32_e32 v16, 16, v21
	v_and_b32_e32 v17, 0xffff0000, v21
	v_pk_fma_f32 v[8:9], v[82:83], v[16:17], v[8:9]
	v_lshlrev_b32_e32 v16, 16, v5
	v_and_b32_e32 v17, 0xffff0000, v5
	v_pk_fma_f32 v[8:9], v[86:87], v[16:17], v[8:9]
	v_and_b32_e32 v21, 0xffff0000, v18
	v_mul_f32_e32 v5, 0xbfb8aa3b, v8
	v_exp_f32_e32 v5, v5
	v_pk_fma_f32 v[20:21], v[28:29], v[20:21], 0 op_sel_hi:[1,1,0]
	v_lshlrev_b32_e32 v28, 16, v10
	v_and_b32_e32 v29, 0xffff0000, v10
	v_add_f32_e32 v5, 1.0, v5
	v_rcp_f32_e32 v16, v5
	v_mul_f32_e32 v5, 0xbfb8aa3b, v9
	v_exp_f32_e32 v5, v5
	v_pk_fma_f32 v[20:21], v[24:25], v[28:29], v[20:21]
	v_lshlrev_b32_e32 v24, 16, v22
	v_and_b32_e32 v25, 0xffff0000, v22
	v_pk_fma_f32 v[12:13], v[12:13], v[24:25], v[20:21]
	v_lshlrev_b32_e32 v20, 16, v6
	v_and_b32_e32 v21, 0xffff0000, v6
	v_add_f32_e32 v5, 1.0, v5
	s_waitcnt lgkmcnt(0)
	v_pk_fma_f32 v[0:1], v[0:1], v[20:21], v[12:13]
	v_rcp_f32_e32 v17, v5
	v_mul_f32_e32 v5, 0xbfb8aa3b, v0
	v_exp_f32_e32 v5, v5
	v_lshlrev_b32_e32 v18, 16, v19
	v_and_b32_e32 v19, 0xffff0000, v19
	v_pk_fma_f32 v[18:19], v[30:31], v[18:19], 0 op_sel_hi:[1,1,0]
	v_add_f32_e32 v5, 1.0, v5
	v_rcp_f32_e32 v12, v5
	v_mul_f32_e32 v5, 0xbfb8aa3b, v1
	v_exp_f32_e32 v5, v5
	v_lshlrev_b32_e32 v10, 16, v11
	v_and_b32_e32 v11, 0xffff0000, v11
	v_pk_fma_f32 v[10:11], v[26:27], v[10:11], v[18:19]
	v_lshlrev_b32_e32 v18, 16, v23
	v_and_b32_e32 v19, 0xffff0000, v23
	v_pk_fma_f32 v[10:11], v[14:15], v[18:19], v[10:11]
	v_lshlrev_b32_e32 v6, 16, v7
	v_and_b32_e32 v7, 0xffff0000, v7
	v_add_f32_e32 v5, 1.0, v5
	v_pk_fma_f32 v[2:3], v[2:3], v[6:7], v[10:11]
	v_rcp_f32_e32 v13, v5
	v_mul_f32_e32 v5, 0xbfb8aa3b, v2
	v_exp_f32_e32 v5, v5
	v_pk_mul_f32 v[32:33], v[32:33], v[34:35]
	v_pk_mul_f32 v[8:9], v[8:9], v[16:17]
	v_pk_mul_f32 v[34:35], v[32:33], v[32:33]
	v_add_f32_e32 v5, 1.0, v5
	v_rcp_f32_e32 v6, v5
	v_mul_f32_e32 v5, 0xbfb8aa3b, v3
	v_exp_f32_e32 v5, v5
	v_pk_mul_f32 v[16:17], v[8:9], v[8:9]
	v_pk_mul_f32 v[0:1], v[0:1], v[12:13]
	v_add_f32_e32 v5, 1.0, v5
	v_rcp_f32_e32 v7, v5
	v_add_f32_e32 v5, v34, v35
	v_add_f32_e32 v5, v16, v5
	v_pk_mul_f32 v[12:13], v[0:1], v[0:1]
	v_add_f32_e32 v5, v17, v5
	v_pk_mul_f32 v[2:3], v[2:3], v[6:7]
	v_add_f32_e32 v5, v12, v5
	v_pk_mul_f32 v[6:7], v[2:3], v[2:3]
	v_add_f32_e32 v5, v13, v5
	v_add_f32_e32 v5, v6, v5
	v_add_f32_e32 v5, v7, v5
	s_nop 1
	v_add_f32_dpp v5, v5, v5 quad_perm:[1,0,3,2] row_mask:0xf bank_mask:0xf
	s_nop 1
	v_add_f32_dpp v5, v5, v5 quad_perm:[2,3,0,1] row_mask:0xf bank_mask:0xf
	s_nop 1
	v_add_f32_dpp v5, v5, v5 row_half_mirror row_mask:0xf bank_mask:0xf
	s_nop 1
	v_mov_b32_dpp v6, v5 row_mirror row_mask:0xf bank_mask:0xf
	s_and_saveexec_b64 s[22:23], vcc
	s_cbranch_execz .Ls1t4_762
	s_waitcnt lgkmcnt(0)
	v_add_f32_e32 v4, v5, v6
	v_add_f32_e32 v4, 0x358637bd, v4
	v_mul_f32_e32 v5, 0x4b800000, v4
	v_cmp_gt_f32_e32 vcc, s34, v4
	s_nop 1
	v_cndmask_b32_e32 v4, v4, v5, vcc
	v_rsq_f32_e32 v4, v4
	s_nop 0
	v_mul_f32_e32 v5, 0x45800000, v4
	v_cndmask_b32_e32 v4, v4, v5, vcc
	v_cmp_gt_u32_e32 vcc, s30, v112
	s_nop 1
	v_cndmask_b32_e32 v5, 1.0, v231, vcc
	v_mul_f32_e32 v4, v5, v4
; #define LAS __attribute__((address_space(3)))
; __device__ __forceinline__ float lo_bf(unsigned w) { return __uint_as_float(w << 16); }
; __device__ __forceinline__ float hi_bf(unsigned w) { return __uint_as_float(w & 0xffff0000u); }
; __device__ __forceinline__ unsigned pk2(float lo, float hi) { const f32x2_t v = {lo, hi}; const bf16x2_t b = __builtin_convertvector(v, bf16x2_t); return __builtin_bit_cast(unsigned, b); }
; __device__ __forceinline__ float silu_(float x) { return x * sigm(x); }
; __device__ __forceinline__ void dn_prep_item(const Args& a, LAS unsigned char* lds, int item, int tid, int wave, int lane, int& cwh, int next_item) {
;     ...
;         float o[8];
; #pragma unroll
;         for (int q = 0; q < 8; ++q) o[q] = 0.f;
; #pragma unroll
;         for (int jj = 0; jj < 4; ++jj) { const v4u v = xv[jj];
;             const f32x4 w0 = *(const LAS f32x4*)(cwl + (which * 4 + jj) * 128 + 8 * gq), w1 = *(const LAS f32x4*)(cwl + (which * 4 + jj) * 128 + 8 * gq + 4);
;             o[0] += w0[0] * lo_bf(v.x); o[1] += w0[1] * hi_bf(v.x); o[2] += w0[2] * lo_bf(v.y); o[3] += w0[3] * hi_bf(v.y);
;             o[4] += w1[0] * lo_bf(v.z); o[5] += w1[1] * hi_bf(v.z); o[6] += w1[2] * lo_bf(v.w); o[7] += w1[3] * hi_bf(v.w); }
;         float s = 0.f;
; #pragma unroll
;         for (int q = 0; q < 8; ++q) { o[q] = silu_(o[q]); s += o[q] * o[q]; }
;         s += __shfl_xor(s, 1); s += __shfl_xor(s, 2); s += __shfl_xor(s, 4); s += __shfl_xor(s, 8);
;         const float inv = which == 2 ? 1.0f : rsqrtf(s + EPS) * (which == 0 ? 0.08838834764831845f : 1.0f);
;         v4u w; w.x = pk2(o[0] * inv, o[1] * inv); w.y = pk2(o[2] * inv, o[3] * inv); w.z = pk2(o[4] * inv, o[5] * inv); w.w = pk2(o[6] * inv, o[7] * inv);
;         *(LAS v4u*)(lds + (which == 0 ? L_QS : which == 1 ? L_KH : L_V) + i * KS_ + 16 * gq) = w;
.Ls1t4_762:
	s_or_b64 exec, exec, s[22:23]
	v_pk_mul_f32 v[0:1], v[0:1], v[4:5] op_sel_hi:[1,0]
	v_cmp_eq_u32_e32 vcc, 1, v114
	v_cvt_pk_bf16_f32 v12, v0, v1
	v_pk_mul_f32 v[0:1], v[2:3], v[4:5] op_sel_hi:[1,0]
	s_waitcnt lgkmcnt(0)
	v_pk_mul_f32 v[6:7], v[32:33], v[4:5] op_sel_hi:[1,0]
	v_cvt_pk_bf16_f32 v13, v0, v1
	v_cndmask_b32_e64 v0, v188, 0, vcc
	v_cmp_lt_u32_e32 vcc, s31, v112
	v_cvt_pk_bf16_f32 v10, v6, v7
	v_pk_mul_f32 v[6:7], v[8:9], v[4:5] op_sel_hi:[1,0]
	v_cndmask_b32_e32 v0, v232, v0, vcc
	v_add_u32_e32 v0, 0, v0
	v_mul_u32_u24_e32 v1, 0x110, v113
	v_cvt_pk_bf16_f32 v11, v6, v7
	v_add3_u32 v0, v0, v1, v151
	ds_write_b128 v0, v[10:13]
	v_lshl_add_u32 v0, v109, 11, v150
	ds_read_b128 v[44:47], v0
	ds_read_b128 v[28:31], v0 offset:16
	ds_read_b128 v[72:75], v0 offset:512
	ds_read_b128 v[24:27], v0 offset:528
	ds_read_b128 v[76:79], v0 offset:1024
	ds_read_b128 v[96:99], v0 offset:1040
	ds_read_b128 v[80:83], v0 offset:1536
	ds_read_b128 v[0:3], v0 offset:1552
	s_waitcnt vmcnt(3)
	v_lshlrev_b32_e32 v32, 16, v100
	v_and_b32_e32 v33, 0xffff0000, v100
	s_waitcnt lgkmcnt(7)
	v_pk_fma_f32 v[32:33], v[44:45], v[32:33], 0 op_sel_hi:[1,1,0]
	s_waitcnt vmcnt(2)
	v_lshlrev_b32_e32 v34, 16, v92
	v_and_b32_e32 v35, 0xffff0000, v92
	s_waitcnt lgkmcnt(5)
	v_pk_fma_f32 v[32:33], v[72:73], v[34:35], v[32:33]
	s_waitcnt vmcnt(1)
	v_lshlrev_b32_e32 v34, 16, v104
	v_and_b32_e32 v35, 0xffff0000, v104
	s_waitcnt lgkmcnt(3)
	v_pk_fma_f32 v[32:33], v[76:77], v[34:35], v[32:33]
	v_lshlrev_b32_e32 v100, 16, v101
	v_and_b32_e32 v101, 0xffff0000, v101
	v_pk_fma_f32 v[100:101], v[46:47], v[100:101], 0 op_sel_hi:[1,1,0]
	v_lshlrev_b32_e32 v104, 16, v102
	v_cmp_ne_u32_e32 vcc, 2, v109
	s_waitcnt vmcnt(0)
	v_lshlrev_b32_e32 v34, 16, v88
	v_and_b32_e32 v35, 0xffff0000, v88
	s_waitcnt lgkmcnt(1)
	v_pk_fma_f32 v[32:33], v[80:81], v[34:35], v[32:33]
	s_nop 0
	v_mul_f32_e32 v88, 0xbfb8aa3b, v32
	v_exp_f32_e32 v92, v88
	v_mov_b32_e32 v88, 1.0
	v_add_f32_e32 v92, 1.0, v92
	v_rcp_f32_e32 v34, v92
	v_mul_f32_e32 v92, 0xbfb8aa3b, v33
	v_exp_f32_e32 v92, v92
	s_nop 0
	v_add_f32_e32 v92, 1.0, v92
	v_rcp_f32_e32 v35, v92
	v_lshlrev_b32_e32 v92, 16, v93
	v_and_b32_e32 v93, 0xffff0000, v93
	v_pk_fma_f32 v[92:93], v[74:75], v[92:93], v[100:101]
	v_lshlrev_b32_e32 v100, 16, v105
	v_and_b32_e32 v101, 0xffff0000, v105
	v_pk_fma_f32 v[92:93], v[78:79], v[100:101], v[92:93]
	v_lshlrev_b32_e32 v100, 16, v89
	v_and_b32_e32 v101, 0xffff0000, v89
	v_pk_fma_f32 v[92:93], v[82:83], v[100:101], v[92:93]
	v_and_b32_e32 v105, 0xffff0000, v102
	v_mul_f32_e32 v89, 0xbfb8aa3b, v92
	v_exp_f32_e32 v89, v89
	v_pk_fma_f32 v[104:105], v[28:29], v[104:105], 0 op_sel_hi:[1,1,0]
	v_lshlrev_b32_e32 v28, 16, v94
	v_and_b32_e32 v29, 0xffff0000, v94
	v_add_f32_e32 v89, 1.0, v89
	v_rcp_f32_e32 v100, v89
	v_mul_f32_e32 v89, 0xbfb8aa3b, v93
	v_exp_f32_e32 v89, v89
	v_pk_fma_f32 v[104:105], v[24:25], v[28:29], v[104:105]
	v_lshlrev_b32_e32 v24, 16, v106
	v_and_b32_e32 v25, 0xffff0000, v106
	v_pk_fma_f32 v[96:97], v[96:97], v[24:25], v[104:105]
	v_lshlrev_b32_e32 v104, 16, v90
	v_and_b32_e32 v105, 0xffff0000, v90
	v_add_f32_e32 v89, 1.0, v89
	s_waitcnt lgkmcnt(0)
	v_pk_fma_f32 v[0:1], v[0:1], v[104:105], v[96:97]
	v_rcp_f32_e32 v101, v89
	v_mul_f32_e32 v89, 0xbfb8aa3b, v0
	v_exp_f32_e32 v89, v89
	v_lshlrev_b32_e32 v102, 16, v103
	v_and_b32_e32 v103, 0xffff0000, v103
	v_pk_fma_f32 v[102:103], v[30:31], v[102:103], 0 op_sel_hi:[1,1,0]
	v_add_f32_e32 v89, 1.0, v89
	v_rcp_f32_e32 v96, v89
	v_mul_f32_e32 v89, 0xbfb8aa3b, v1
	v_exp_f32_e32 v89, v89
	v_lshlrev_b32_e32 v94, 16, v95
	v_and_b32_e32 v95, 0xffff0000, v95
	v_pk_fma_f32 v[94:95], v[26:27], v[94:95], v[102:103]
	v_lshlrev_b32_e32 v102, 16, v107
	v_and_b32_e32 v103, 0xffff0000, v107
	v_pk_fma_f32 v[94:95], v[98:99], v[102:103], v[94:95]
	v_lshlrev_b32_e32 v90, 16, v91
	v_and_b32_e32 v91, 0xffff0000, v91
	v_add_f32_e32 v89, 1.0, v89
	v_pk_fma_f32 v[2:3], v[2:3], v[90:91], v[94:95]
	v_rcp_f32_e32 v97, v89
	v_mul_f32_e32 v89, 0xbfb8aa3b, v2
	v_exp_f32_e32 v89, v89
	v_pk_mul_f32 v[32:33], v[32:33], v[34:35]
	v_pk_mul_f32 v[92:93], v[92:93], v[100:101]
	v_pk_mul_f32 v[34:35], v[32:33], v[32:33]
	v_add_f32_e32 v89, 1.0, v89
	v_rcp_f32_e32 v90, v89
	v_mul_f32_e32 v89, 0xbfb8aa3b, v3
	v_exp_f32_e32 v89, v89
	v_pk_mul_f32 v[100:101], v[92:93], v[92:93]
	v_pk_mul_f32 v[0:1], v[0:1], v[96:97]
	v_add_f32_e32 v89, 1.0, v89
	v_rcp_f32_e32 v91, v89
	v_add_f32_e32 v89, v34, v35
	v_add_f32_e32 v89, v100, v89
	v_pk_mul_f32 v[96:97], v[0:1], v[0:1]
	v_add_f32_e32 v89, v101, v89
	v_pk_mul_f32 v[2:3], v[2:3], v[90:91]
	v_add_f32_e32 v89, v96, v89
	v_pk_mul_f32 v[90:91], v[2:3], v[2:3]
	v_add_f32_e32 v89, v97, v89
	v_add_f32_e32 v89, v90, v89
	v_add_f32_e32 v89, v91, v89
	s_nop 1
	v_add_f32_dpp v89, v89, v89 quad_perm:[1,0,3,2] row_mask:0xf bank_mask:0xf
	s_nop 1
	v_add_f32_dpp v89, v89, v89 quad_perm:[2,3,0,1] row_mask:0xf bank_mask:0xf
	s_nop 1
	v_add_f32_dpp v89, v89, v89 row_half_mirror row_mask:0xf bank_mask:0xf
	s_nop 1
	v_mov_b32_dpp v90, v89 row_mirror row_mask:0xf bank_mask:0xf
	s_and_saveexec_b64 s[22:23], vcc
	s_cbranch_execz .Ls1t5_745
	s_waitcnt lgkmcnt(0)
	v_add_f32_e32 v88, v89, v90
	v_add_f32_e32 v88, 0x358637bd, v88
	v_mul_f32_e32 v89, 0x4b800000, v88
	v_cmp_gt_f32_e32 vcc, s34, v88
	s_nop 1
	v_cndmask_b32_e32 v88, v88, v89, vcc
	v_rsq_f32_e32 v88, v88
	s_nop 0
	v_mul_f32_e32 v89, 0x45800000, v88
	v_cndmask_b32_e32 v88, v88, v89, vcc
